# fused-RMSNorm GEMM epilogues: throw-away loads over the residual tile lines issued right after the K-loop (L2 warm-up before the real residual loads)
# baseline (speedup 1.0000x reference)
.LBB0_741:
	s_add_u32 s12, s36, 0xfff80080
	s_addc_u32 s13, s37, -1
	s_add_i32 s14, 0, 0x10000
	s_cmp_eq_u32 s11, 28
	s_cselect_b32 s63, s5, s13
	s_cselect_b32 s62, s6, s12
	s_cselect_b32 s39, s7, s10
	s_cselect_b32 s38, s8, s9
	s_add_i32 s15, 0, 0x14000
	v_add_u32_e32 v144, s14, v230
	v_add_u32_e32 v160, s15, v230
	ds_read_b128 v[124:127], v144
	ds_read_b128 v[128:131], v144 offset:1024
	ds_read_b128 v[136:139], v144 offset:2048
	ds_read_b128 v[144:147], v144 offset:3072
	ds_read_b128 v[148:151], v160
	ds_read_b128 v[152:155], v160 offset:1024
	ds_read_b128 v[156:159], v160 offset:2048
	ds_read_b128 v[160:163], v160 offset:3072
	v_lshl_add_u64 v[196:197], s[36:37], 0, v[222:223]
	s_add_i32 m0, s21, 0xc000
	ds_read_b128 v[164:167], v243
	ds_read_b128 v[168:171], v243 offset:1024
	ds_read_b128 v[172:175], v243 offset:2048
	ds_read_b128 v[176:179], v243 offset:3072
	ds_read_b128 v[180:183], v243 offset:4096
	ds_read_b128 v[184:187], v243 offset:5120
	ds_read_b128 v[188:191], v243 offset:6144
	ds_read_b128 v[192:195], v243 offset:7168
	global_load_lds_dwordx4 v[196:197], off
	v_lshl_add_u64 v[196:197], s[36:37], 0, v[220:221]
	s_add_i32 m0, s21, 0xe000
	s_nop 0
	global_load_lds_dwordx4 v[196:197], off
	s_waitcnt vmcnt(8)
	s_waitcnt lgkmcnt(0)
	s_barrier
	s_setprio 1
	s_waitcnt lgkmcnt(0)
	v_mfma_f32_16x16x32_bf16 v[140:143], v[124:127], v[164:167], v[140:143]
	v_mfma_f32_16x16x32_bf16 v[132:135], v[136:139], v[164:167], v[132:135]
	v_mfma_f32_16x16x32_bf16 v[112:115], v[124:127], v[172:175], v[112:115]
	v_mfma_f32_16x16x32_bf16 v[108:111], v[136:139], v[172:175], v[108:111]
	v_mfma_f32_16x16x32_bf16 v[96:99], v[124:127], v[180:183], v[96:99]
	v_mfma_f32_16x16x32_bf16 v[92:95], v[136:139], v[180:183], v[92:95]
	v_mfma_f32_16x16x32_bf16 v[80:83], v[124:127], v[188:191], v[80:83]
	v_mfma_f32_16x16x32_bf16 v[76:79], v[136:139], v[188:191], v[76:79]
	v_mfma_f32_16x16x32_bf16 v[140:143], v[128:131], v[168:171], v[140:143]
	v_mfma_f32_16x16x32_bf16 v[132:135], v[144:147], v[168:171], v[132:135]
	v_mfma_f32_16x16x32_bf16 v[112:115], v[128:131], v[176:179], v[112:115]
	v_mfma_f32_16x16x32_bf16 v[108:111], v[144:147], v[176:179], v[108:111]
	v_mfma_f32_16x16x32_bf16 v[96:99], v[128:131], v[184:187], v[96:99]
	v_mfma_f32_16x16x32_bf16 v[92:95], v[144:147], v[184:187], v[92:95]
	v_mfma_f32_16x16x32_bf16 v[80:83], v[128:131], v[192:195], v[80:83]
	v_mfma_f32_16x16x32_bf16 v[76:79], v[144:147], v[192:195], v[76:79]
	s_setprio 0
	s_setprio 1
	v_mfma_f32_16x16x32_bf16 v[120:123], v[148:151], v[164:167], v[120:123]
	v_mfma_f32_16x16x32_bf16 v[116:119], v[156:159], v[164:167], v[116:119]
	v_mfma_f32_16x16x32_bf16 v[104:107], v[148:151], v[172:175], v[104:107]
	v_mfma_f32_16x16x32_bf16 v[100:103], v[156:159], v[172:175], v[100:103]
	v_mfma_f32_16x16x32_bf16 v[88:91], v[148:151], v[180:183], v[88:91]
	v_mfma_f32_16x16x32_bf16 v[84:87], v[156:159], v[180:183], v[84:87]
	v_mfma_f32_16x16x32_bf16 v[72:75], v[148:151], v[188:191], v[72:75]
	v_mfma_f32_16x16x32_bf16 v[68:71], v[156:159], v[188:191], v[68:71]
	v_mfma_f32_16x16x32_bf16 v[120:123], v[152:155], v[168:171], v[120:123]
	v_mfma_f32_16x16x32_bf16 v[116:119], v[160:163], v[168:171], v[116:119]
	v_mfma_f32_16x16x32_bf16 v[104:107], v[152:155], v[176:179], v[104:107]
	v_mfma_f32_16x16x32_bf16 v[100:103], v[160:163], v[176:179], v[100:103]
	v_mfma_f32_16x16x32_bf16 v[88:91], v[152:155], v[184:187], v[88:91]
	v_mfma_f32_16x16x32_bf16 v[84:87], v[160:163], v[184:187], v[84:87]
	v_mfma_f32_16x16x32_bf16 v[72:75], v[152:155], v[192:195], v[72:75]
	v_mfma_f32_16x16x32_bf16 v[68:71], v[160:163], v[192:195], v[68:71]
	s_setprio 0
	s_barrier
	s_add_i32 s12, s14, s82
	v_lshl_add_u64 v[196:197], s[38:39], 0, v[2:3]
	s_mov_b32 m0, s12
	ds_read_b128 v[164:167], v243 offset:16384
	ds_read_b128 v[168:171], v243 offset:17408
	ds_read_b128 v[172:175], v243 offset:18432
	ds_read_b128 v[176:179], v243 offset:19456
	ds_read_b128 v[180:183], v243 offset:20480
	ds_read_b128 v[184:187], v243 offset:21504
	ds_read_b128 v[188:191], v243 offset:22528
	ds_read_b128 v[192:195], v243 offset:23552
	global_load_lds_dwordx4 v[196:197], off
	s_add_i32 m0, s12, 0x2000
	s_add_u32 s12, s38, 0x80000
	v_lshl_add_u64 v[198:199], s[38:39], 0, v[218:219]
	s_addc_u32 s13, s39, 0
	s_add_i32 s14, s15, s82
	global_load_lds_dwordx4 v[198:199], off
	v_lshl_add_u64 v[200:201], s[12:13], 0, v[2:3]
	s_mov_b32 m0, s14
	v_lshl_add_u64 v[202:203], s[62:63], 0, v[216:217]
	global_load_lds_dwordx4 v[200:201], off
	v_lshl_add_u64 v[200:201], s[12:13], 0, v[218:219]
	s_add_i32 m0, s14, 0x2000
	s_nop 0
	global_load_lds_dwordx4 v[200:201], off
	v_lshl_add_u64 v[200:201], s[62:63], 0, v[0:1]
	s_mov_b32 m0, s21
	s_nop 0
	global_load_lds_dwordx4 v[200:201], off
	s_mov_b32 m0, s83
	s_nop 0
	global_load_lds_dwordx4 v[202:203], off
	s_waitcnt vmcnt(8)
	s_waitcnt lgkmcnt(0)
	s_barrier
	s_setprio 1
	s_waitcnt lgkmcnt(0)
	v_mfma_f32_16x16x32_bf16 v[64:67], v[124:127], v[164:167], v[64:67]
	v_mfma_f32_16x16x32_bf16 v[60:63], v[136:139], v[164:167], v[60:63]
	v_mfma_f32_16x16x32_bf16 v[48:51], v[124:127], v[172:175], v[48:51]
	v_mfma_f32_16x16x32_bf16 v[44:47], v[136:139], v[172:175], v[44:47]
	v_mfma_f32_16x16x32_bf16 v[32:35], v[124:127], v[180:183], v[32:35]
	v_mfma_f32_16x16x32_bf16 v[28:31], v[136:139], v[180:183], v[28:31]
	v_mfma_f32_16x16x32_bf16 v[16:19], v[124:127], v[188:191], v[16:19]
	v_mfma_f32_16x16x32_bf16 v[12:15], v[136:139], v[188:191], v[12:15]
	v_mfma_f32_16x16x32_bf16 v[64:67], v[128:131], v[168:171], v[64:67]
	v_mfma_f32_16x16x32_bf16 v[60:63], v[144:147], v[168:171], v[60:63]
	v_mfma_f32_16x16x32_bf16 v[48:51], v[128:131], v[176:179], v[48:51]
	v_mfma_f32_16x16x32_bf16 v[44:47], v[144:147], v[176:179], v[44:47]
	v_mfma_f32_16x16x32_bf16 v[32:35], v[128:131], v[184:187], v[32:35]
	v_mfma_f32_16x16x32_bf16 v[28:31], v[144:147], v[184:187], v[28:31]
	v_mfma_f32_16x16x32_bf16 v[16:19], v[128:131], v[192:195], v[16:19]
	v_mfma_f32_16x16x32_bf16 v[12:15], v[144:147], v[192:195], v[12:15]
	s_setprio 0
	s_setprio 1
	v_mfma_f32_16x16x32_bf16 v[56:59], v[148:151], v[164:167], v[56:59]
	v_mfma_f32_16x16x32_bf16 v[52:55], v[156:159], v[164:167], v[52:55]
	v_mfma_f32_16x16x32_bf16 v[40:43], v[148:151], v[172:175], v[40:43]
	v_mfma_f32_16x16x32_bf16 v[36:39], v[156:159], v[172:175], v[36:39]
	v_mfma_f32_16x16x32_bf16 v[24:27], v[148:151], v[180:183], v[24:27]
	v_mfma_f32_16x16x32_bf16 v[20:23], v[156:159], v[180:183], v[20:23]
	v_mfma_f32_16x16x32_bf16 v[8:11], v[148:151], v[188:191], v[8:11]
	v_mfma_f32_16x16x32_bf16 v[4:7], v[156:159], v[188:191], v[4:7]
	v_mfma_f32_16x16x32_bf16 v[56:59], v[152:155], v[168:171], v[56:59]
	v_mfma_f32_16x16x32_bf16 v[52:55], v[160:163], v[168:171], v[52:55]
	v_mfma_f32_16x16x32_bf16 v[40:43], v[152:155], v[176:179], v[40:43]
	v_mfma_f32_16x16x32_bf16 v[36:39], v[160:163], v[176:179], v[36:39]
	v_mfma_f32_16x16x32_bf16 v[24:27], v[152:155], v[184:187], v[24:27]
	v_mfma_f32_16x16x32_bf16 v[20:23], v[160:163], v[184:187], v[20:23]
	v_mfma_f32_16x16x32_bf16 v[8:11], v[152:155], v[192:195], v[8:11]
	v_mfma_f32_16x16x32_bf16 v[4:7], v[160:163], v[192:195], v[4:7]
	s_setprio 0
	s_barrier
	s_add_i32 s14, 0, 0x18000
	s_add_i32 s15, 0, 0x1c000
	v_add_u32_e32 v144, s14, v230
	v_add_u32_e32 v160, s15, v230
	ds_read_b128 v[124:127], v144
	ds_read_b128 v[128:131], v144 offset:1024
	ds_read_b128 v[136:139], v144 offset:2048
	ds_read_b128 v[144:147], v144 offset:3072
	ds_read_b128 v[148:151], v160
	ds_read_b128 v[152:155], v160 offset:1024
	ds_read_b128 v[156:159], v160 offset:2048
	ds_read_b128 v[160:163], v160 offset:3072
	s_add_u32 s12, s62, 0x80000
	s_addc_u32 s13, s63, 0
	s_mov_b32 m0, s84
	v_lshl_add_u64 v[204:205], s[12:13], 0, v[0:1]
	ds_read_b128 v[164:167], v243 offset:32768
	ds_read_b128 v[168:171], v243 offset:33792
	ds_read_b128 v[172:175], v243 offset:34816
	ds_read_b128 v[176:179], v243 offset:35840
	ds_read_b128 v[180:183], v243 offset:36864
	ds_read_b128 v[184:187], v243 offset:37888
	ds_read_b128 v[188:191], v243 offset:38912
	ds_read_b128 v[192:195], v243 offset:39936
	global_load_lds_dwordx4 v[204:205], off
	v_lshl_add_u64 v[204:205], s[12:13], 0, v[216:217]
	s_mov_b32 m0, s85
	s_nop 0
	global_load_lds_dwordx4 v[204:205], off
	s_waitcnt vmcnt(8)
	s_waitcnt lgkmcnt(0)
	s_barrier
	s_setprio 1
	s_waitcnt lgkmcnt(0)
	v_mfma_f32_16x16x32_bf16 v[140:143], v[124:127], v[164:167], v[140:143]
	v_mfma_f32_16x16x32_bf16 v[132:135], v[136:139], v[164:167], v[132:135]
	v_mfma_f32_16x16x32_bf16 v[112:115], v[124:127], v[172:175], v[112:115]
	v_mfma_f32_16x16x32_bf16 v[108:111], v[136:139], v[172:175], v[108:111]
	v_mfma_f32_16x16x32_bf16 v[96:99], v[124:127], v[180:183], v[96:99]
	v_mfma_f32_16x16x32_bf16 v[92:95], v[136:139], v[180:183], v[92:95]
	v_mfma_f32_16x16x32_bf16 v[80:83], v[124:127], v[188:191], v[80:83]
	v_mfma_f32_16x16x32_bf16 v[76:79], v[136:139], v[188:191], v[76:79]
	v_mfma_f32_16x16x32_bf16 v[140:143], v[128:131], v[168:171], v[140:143]
	v_mfma_f32_16x16x32_bf16 v[132:135], v[144:147], v[168:171], v[132:135]
	v_mfma_f32_16x16x32_bf16 v[112:115], v[128:131], v[176:179], v[112:115]
	v_mfma_f32_16x16x32_bf16 v[108:111], v[144:147], v[176:179], v[108:111]
	v_mfma_f32_16x16x32_bf16 v[96:99], v[128:131], v[184:187], v[96:99]
	v_mfma_f32_16x16x32_bf16 v[92:95], v[144:147], v[184:187], v[92:95]
	v_mfma_f32_16x16x32_bf16 v[80:83], v[128:131], v[192:195], v[80:83]
	v_mfma_f32_16x16x32_bf16 v[76:79], v[144:147], v[192:195], v[76:79]
	s_setprio 0
	s_setprio 1
	v_mfma_f32_16x16x32_bf16 v[120:123], v[148:151], v[164:167], v[120:123]
	v_mfma_f32_16x16x32_bf16 v[116:119], v[156:159], v[164:167], v[116:119]
	v_mfma_f32_16x16x32_bf16 v[104:107], v[148:151], v[172:175], v[104:107]
	v_mfma_f32_16x16x32_bf16 v[100:103], v[156:159], v[172:175], v[100:103]
	v_mfma_f32_16x16x32_bf16 v[88:91], v[148:151], v[180:183], v[88:91]
	v_mfma_f32_16x16x32_bf16 v[84:87], v[156:159], v[180:183], v[84:87]
	v_mfma_f32_16x16x32_bf16 v[72:75], v[148:151], v[188:191], v[72:75]
	v_mfma_f32_16x16x32_bf16 v[68:71], v[156:159], v[188:191], v[68:71]
	v_mfma_f32_16x16x32_bf16 v[120:123], v[152:155], v[168:171], v[120:123]
	v_mfma_f32_16x16x32_bf16 v[116:119], v[160:163], v[168:171], v[116:119]
	v_mfma_f32_16x16x32_bf16 v[104:107], v[152:155], v[176:179], v[104:107]
	v_mfma_f32_16x16x32_bf16 v[100:103], v[160:163], v[176:179], v[100:103]
	v_mfma_f32_16x16x32_bf16 v[88:91], v[152:155], v[184:187], v[88:91]
	v_mfma_f32_16x16x32_bf16 v[84:87], v[160:163], v[184:187], v[84:87]
	v_mfma_f32_16x16x32_bf16 v[72:75], v[152:155], v[192:195], v[72:75]
	v_mfma_f32_16x16x32_bf16 v[68:71], v[160:163], v[192:195], v[68:71]
	s_setprio 0
	s_barrier
	s_add_i32 s12, s14, s82
	v_lshl_add_u64 v[196:197], v[196:197], 0, s[68:69]
	s_mov_b32 m0, s12
	ds_read_b128 v[164:167], v243 offset:49152
	ds_read_b128 v[168:171], v243 offset:50176
	ds_read_b128 v[172:175], v243 offset:51200
	ds_read_b128 v[176:179], v243 offset:52224
	ds_read_b128 v[180:183], v243 offset:53248
	ds_read_b128 v[184:187], v243 offset:54272
	ds_read_b128 v[188:191], v243 offset:55296
	ds_read_b128 v[192:195], v243 offset:56320
	global_load_lds_dwordx4 v[196:197], off
	s_add_i32 m0, s12, 0x2000
	s_add_u32 s12, s38, 0x80080
	v_lshl_add_u64 v[196:197], v[198:199], 0, s[68:69]
	s_addc_u32 s13, s39, 0
	s_add_i32 s14, s15, s82
	global_load_lds_dwordx4 v[196:197], off
	v_lshl_add_u64 v[196:197], s[12:13], 0, v[2:3]
	s_mov_b32 m0, s14
	s_nop 0
	global_load_lds_dwordx4 v[196:197], off
	v_lshl_add_u64 v[196:197], s[12:13], 0, v[218:219]
	s_add_i32 m0, s14, 0x2000
	s_nop 0
	global_load_lds_dwordx4 v[196:197], off
	v_lshl_add_u64 v[196:197], v[200:201], 0, s[68:69]
	s_mov_b32 m0, s89
	s_nop 0
	global_load_lds_dwordx4 v[196:197], off
	v_lshl_add_u64 v[196:197], v[202:203], 0, s[68:69]
	s_mov_b32 m0, s90
	s_nop 0
	global_load_lds_dwordx4 v[196:197], off
	s_waitcnt vmcnt(8)
	s_waitcnt lgkmcnt(0)
	s_barrier
	s_setprio 1
	s_waitcnt lgkmcnt(0)
	v_mfma_f32_16x16x32_bf16 v[64:67], v[124:127], v[164:167], v[64:67]
	v_mfma_f32_16x16x32_bf16 v[60:63], v[136:139], v[164:167], v[60:63]
	v_mfma_f32_16x16x32_bf16 v[48:51], v[124:127], v[172:175], v[48:51]
	v_mfma_f32_16x16x32_bf16 v[44:47], v[136:139], v[172:175], v[44:47]
	v_mfma_f32_16x16x32_bf16 v[32:35], v[124:127], v[180:183], v[32:35]
	v_mfma_f32_16x16x32_bf16 v[28:31], v[136:139], v[180:183], v[28:31]
	v_mfma_f32_16x16x32_bf16 v[16:19], v[124:127], v[188:191], v[16:19]
	v_mfma_f32_16x16x32_bf16 v[12:15], v[136:139], v[188:191], v[12:15]
	v_mfma_f32_16x16x32_bf16 v[64:67], v[128:131], v[168:171], v[64:67]
	v_mfma_f32_16x16x32_bf16 v[60:63], v[144:147], v[168:171], v[60:63]
	v_mfma_f32_16x16x32_bf16 v[48:51], v[128:131], v[176:179], v[48:51]
	v_mfma_f32_16x16x32_bf16 v[44:47], v[144:147], v[176:179], v[44:47]
	v_mfma_f32_16x16x32_bf16 v[32:35], v[128:131], v[184:187], v[32:35]
	v_mfma_f32_16x16x32_bf16 v[28:31], v[144:147], v[184:187], v[28:31]
	v_mfma_f32_16x16x32_bf16 v[16:19], v[128:131], v[192:195], v[16:19]
	v_mfma_f32_16x16x32_bf16 v[12:15], v[144:147], v[192:195], v[12:15]
	s_setprio 0
	s_setprio 1
	v_mfma_f32_16x16x32_bf16 v[56:59], v[148:151], v[164:167], v[56:59]
	v_mfma_f32_16x16x32_bf16 v[52:55], v[156:159], v[164:167], v[52:55]
	v_mfma_f32_16x16x32_bf16 v[40:43], v[148:151], v[172:175], v[40:43]
	v_mfma_f32_16x16x32_bf16 v[36:39], v[156:159], v[172:175], v[36:39]
	v_mfma_f32_16x16x32_bf16 v[24:27], v[148:151], v[180:183], v[24:27]
	v_mfma_f32_16x16x32_bf16 v[20:23], v[156:159], v[180:183], v[20:23]
	v_mfma_f32_16x16x32_bf16 v[8:11], v[148:151], v[188:191], v[8:11]
	v_mfma_f32_16x16x32_bf16 v[4:7], v[156:159], v[188:191], v[4:7]
	v_mfma_f32_16x16x32_bf16 v[56:59], v[152:155], v[168:171], v[56:59]
	v_mfma_f32_16x16x32_bf16 v[52:55], v[160:163], v[168:171], v[52:55]
	v_mfma_f32_16x16x32_bf16 v[40:43], v[152:155], v[176:179], v[40:43]
	v_mfma_f32_16x16x32_bf16 v[36:39], v[160:163], v[176:179], v[36:39]
	v_mfma_f32_16x16x32_bf16 v[24:27], v[152:155], v[184:187], v[24:27]
	v_mfma_f32_16x16x32_bf16 v[20:23], v[160:163], v[184:187], v[20:23]
	v_mfma_f32_16x16x32_bf16 v[8:11], v[152:155], v[192:195], v[8:11]
	v_mfma_f32_16x16x32_bf16 v[4:7], v[160:163], v[192:195], v[4:7]
	s_setprio 0
	s_barrier
	s_add_i32 s11, s11, 2
	s_add_u32 s9, s9, 0x100
	s_addc_u32 s10, s10, 0
	s_add_u32 s36, s36, 0x100
	s_addc_u32 s37, s37, 0
	s_cmp_gt_u32 s11, 29
	s_cbranch_scc0 .LBB0_741
	s_lshl_b32 s98, s4, 8
	s_add_i32 s98, s98, s87
	s_lshl_b32 s99, s54, 8
	s_or_b32 s99, s99, s88
	v_and_b32_e32 v144, 15, v234
	v_lshrrev_b32_e32 v145, 4, v234
	v_add_u32_e32 v144, s98, v144
	v_lshl_add_u32 v145, v145, 3, s99
	v_lshlrev_b32_e32 v145, 1, v145
	v_lshl_add_u32 v146, v144, 12, v145
	global_load_dword v147, v146, s[26:27]
	global_load_dword v147, v146, s[26:27] offset:256
	s_add_u32 s100, s26, 0x10000
	s_addc_u32 s101, s27, 0
	global_load_dword v147, v146, s[100:101]
	global_load_dword v147, v146, s[100:101] offset:256
	s_add_u32 s100, s26, 0x20000
	s_addc_u32 s101, s27, 0
	global_load_dword v147, v146, s[100:101]
	global_load_dword v147, v146, s[100:101] offset:256
	s_add_u32 s100, s26, 0x30000
	s_addc_u32 s101, s27, 0
	global_load_dword v147, v146, s[100:101]
	global_load_dword v147, v146, s[100:101] offset:256
	s_add_u32 s100, s26, 0x80000
	s_addc_u32 s101, s27, 0
	global_load_dword v147, v146, s[100:101]
	global_load_dword v147, v146, s[100:101] offset:256
	s_add_u32 s100, s26, 0x90000
	s_addc_u32 s101, s27, 0
	global_load_dword v147, v146, s[100:101]
	global_load_dword v147, v146, s[100:101] offset:256
	s_add_u32 s100, s26, 0xa0000
	s_addc_u32 s101, s27, 0
	global_load_dword v147, v146, s[100:101]
	global_load_dword v147, v146, s[100:101] offset:256
	s_add_u32 s100, s26, 0xb0000
	s_addc_u32 s101, s27, 0
	global_load_dword v147, v146, s[100:101]
	global_load_dword v147, v146, s[100:101] offset:256
	s_and_b64 vcc, exec, s[46:47]
	s_cbranch_vccz .LBB0_744
	s_barrier

.LBB0_947:
	s_add_u32 s12, s38, 0xfffc0080
	s_addc_u32 s13, s39, -1
	s_add_i32 s14, 0, 0x10000
	s_cmp_eq_u32 s11, 12
	s_cselect_b32 s57, s5, s13
	s_cselect_b32 s56, s6, s12
	s_cselect_b32 s41, s7, s10
	s_cselect_b32 s40, s8, s9
	s_add_i32 s15, 0, 0x14000
	v_add_u32_e32 v144, s14, v230
	v_add_u32_e32 v160, s15, v230
	ds_read_b128 v[124:127], v144
	ds_read_b128 v[128:131], v144 offset:1024
	ds_read_b128 v[136:139], v144 offset:2048
	ds_read_b128 v[144:147], v144 offset:3072
	ds_read_b128 v[148:151], v160
	ds_read_b128 v[152:155], v160 offset:1024
	ds_read_b128 v[156:159], v160 offset:2048
	ds_read_b128 v[160:163], v160 offset:3072
	v_lshl_add_u64 v[196:197], s[38:39], 0, v[222:223]
	s_add_i32 m0, s71, 0xc000
	ds_read_b128 v[164:167], v243
	ds_read_b128 v[168:171], v243 offset:1024
	ds_read_b128 v[172:175], v243 offset:2048
	ds_read_b128 v[176:179], v243 offset:3072
	ds_read_b128 v[180:183], v243 offset:4096
	ds_read_b128 v[184:187], v243 offset:5120
	ds_read_b128 v[188:191], v243 offset:6144
	ds_read_b128 v[192:195], v243 offset:7168
	global_load_lds_dwordx4 v[196:197], off
	v_lshl_add_u64 v[196:197], s[38:39], 0, v[220:221]
	s_add_i32 m0, s71, 0xe000
	s_nop 0
	global_load_lds_dwordx4 v[196:197], off
	s_waitcnt vmcnt(8)
	s_waitcnt lgkmcnt(0)
	s_barrier
	s_setprio 1
	s_waitcnt lgkmcnt(0)
	v_mfma_f32_16x16x32_bf16 v[140:143], v[124:127], v[164:167], v[140:143]
	v_mfma_f32_16x16x32_bf16 v[132:135], v[136:139], v[164:167], v[132:135]
	v_mfma_f32_16x16x32_bf16 v[112:115], v[124:127], v[172:175], v[112:115]
	v_mfma_f32_16x16x32_bf16 v[108:111], v[136:139], v[172:175], v[108:111]
	v_mfma_f32_16x16x32_bf16 v[96:99], v[124:127], v[180:183], v[96:99]
	v_mfma_f32_16x16x32_bf16 v[92:95], v[136:139], v[180:183], v[92:95]
	v_mfma_f32_16x16x32_bf16 v[80:83], v[124:127], v[188:191], v[80:83]
	v_mfma_f32_16x16x32_bf16 v[76:79], v[136:139], v[188:191], v[76:79]
	v_mfma_f32_16x16x32_bf16 v[140:143], v[128:131], v[168:171], v[140:143]
	v_mfma_f32_16x16x32_bf16 v[132:135], v[144:147], v[168:171], v[132:135]
	v_mfma_f32_16x16x32_bf16 v[112:115], v[128:131], v[176:179], v[112:115]
	v_mfma_f32_16x16x32_bf16 v[108:111], v[144:147], v[176:179], v[108:111]
	v_mfma_f32_16x16x32_bf16 v[96:99], v[128:131], v[184:187], v[96:99]
	v_mfma_f32_16x16x32_bf16 v[92:95], v[144:147], v[184:187], v[92:95]
	v_mfma_f32_16x16x32_bf16 v[80:83], v[128:131], v[192:195], v[80:83]
	v_mfma_f32_16x16x32_bf16 v[76:79], v[144:147], v[192:195], v[76:79]
	s_setprio 0
	s_setprio 1
	v_mfma_f32_16x16x32_bf16 v[120:123], v[148:151], v[164:167], v[120:123]
	v_mfma_f32_16x16x32_bf16 v[116:119], v[156:159], v[164:167], v[116:119]
	v_mfma_f32_16x16x32_bf16 v[104:107], v[148:151], v[172:175], v[104:107]
	v_mfma_f32_16x16x32_bf16 v[100:103], v[156:159], v[172:175], v[100:103]
	v_mfma_f32_16x16x32_bf16 v[88:91], v[148:151], v[180:183], v[88:91]
	v_mfma_f32_16x16x32_bf16 v[84:87], v[156:159], v[180:183], v[84:87]
	v_mfma_f32_16x16x32_bf16 v[72:75], v[148:151], v[188:191], v[72:75]
	v_mfma_f32_16x16x32_bf16 v[68:71], v[156:159], v[188:191], v[68:71]
	v_mfma_f32_16x16x32_bf16 v[120:123], v[152:155], v[168:171], v[120:123]
	v_mfma_f32_16x16x32_bf16 v[116:119], v[160:163], v[168:171], v[116:119]
	v_mfma_f32_16x16x32_bf16 v[104:107], v[152:155], v[176:179], v[104:107]
	v_mfma_f32_16x16x32_bf16 v[100:103], v[160:163], v[176:179], v[100:103]
	v_mfma_f32_16x16x32_bf16 v[88:91], v[152:155], v[184:187], v[88:91]
	v_mfma_f32_16x16x32_bf16 v[84:87], v[160:163], v[184:187], v[84:87]
	v_mfma_f32_16x16x32_bf16 v[72:75], v[152:155], v[192:195], v[72:75]
	v_mfma_f32_16x16x32_bf16 v[68:71], v[160:163], v[192:195], v[68:71]
	s_setprio 0
	s_barrier
	s_add_i32 s12, s14, s70
	v_lshl_add_u64 v[196:197], s[40:41], 0, v[2:3]
	s_mov_b32 m0, s12
	ds_read_b128 v[164:167], v243 offset:16384
	ds_read_b128 v[168:171], v243 offset:17408
	ds_read_b128 v[172:175], v243 offset:18432
	ds_read_b128 v[176:179], v243 offset:19456
	ds_read_b128 v[180:183], v243 offset:20480
	ds_read_b128 v[184:187], v243 offset:21504
	ds_read_b128 v[188:191], v243 offset:22528
	ds_read_b128 v[192:195], v243 offset:23552
	global_load_lds_dwordx4 v[196:197], off
	s_add_i32 m0, s12, 0x2000
	s_add_u32 s12, s40, 0x40000
	v_lshl_add_u64 v[198:199], s[40:41], 0, v[218:219]
	s_addc_u32 s13, s41, 0
	s_add_i32 s14, s15, s70
	global_load_lds_dwordx4 v[198:199], off
	v_lshl_add_u64 v[200:201], s[12:13], 0, v[2:3]
	s_mov_b32 m0, s14
	v_lshl_add_u64 v[202:203], s[56:57], 0, v[216:217]
	global_load_lds_dwordx4 v[200:201], off
	v_lshl_add_u64 v[200:201], s[12:13], 0, v[218:219]
	s_add_i32 m0, s14, 0x2000
	s_nop 0
	global_load_lds_dwordx4 v[200:201], off
	v_lshl_add_u64 v[200:201], s[56:57], 0, v[0:1]
	s_mov_b32 m0, s71
	s_nop 0
	global_load_lds_dwordx4 v[200:201], off
	s_mov_b32 m0, s80
	s_nop 0
	global_load_lds_dwordx4 v[202:203], off
	s_waitcnt vmcnt(8)
	s_waitcnt lgkmcnt(0)
	s_barrier
	s_setprio 1
	s_waitcnt lgkmcnt(0)
	v_mfma_f32_16x16x32_bf16 v[64:67], v[124:127], v[164:167], v[64:67]
	v_mfma_f32_16x16x32_bf16 v[60:63], v[136:139], v[164:167], v[60:63]
	v_mfma_f32_16x16x32_bf16 v[48:51], v[124:127], v[172:175], v[48:51]
	v_mfma_f32_16x16x32_bf16 v[44:47], v[136:139], v[172:175], v[44:47]
	v_mfma_f32_16x16x32_bf16 v[32:35], v[124:127], v[180:183], v[32:35]
	v_mfma_f32_16x16x32_bf16 v[28:31], v[136:139], v[180:183], v[28:31]
	v_mfma_f32_16x16x32_bf16 v[16:19], v[124:127], v[188:191], v[16:19]
	v_mfma_f32_16x16x32_bf16 v[12:15], v[136:139], v[188:191], v[12:15]
	v_mfma_f32_16x16x32_bf16 v[64:67], v[128:131], v[168:171], v[64:67]
	v_mfma_f32_16x16x32_bf16 v[60:63], v[144:147], v[168:171], v[60:63]
	v_mfma_f32_16x16x32_bf16 v[48:51], v[128:131], v[176:179], v[48:51]
	v_mfma_f32_16x16x32_bf16 v[44:47], v[144:147], v[176:179], v[44:47]
	v_mfma_f32_16x16x32_bf16 v[32:35], v[128:131], v[184:187], v[32:35]
	v_mfma_f32_16x16x32_bf16 v[28:31], v[144:147], v[184:187], v[28:31]
	v_mfma_f32_16x16x32_bf16 v[16:19], v[128:131], v[192:195], v[16:19]
	v_mfma_f32_16x16x32_bf16 v[12:15], v[144:147], v[192:195], v[12:15]
	s_setprio 0
	s_setprio 1
	v_mfma_f32_16x16x32_bf16 v[56:59], v[148:151], v[164:167], v[56:59]
	v_mfma_f32_16x16x32_bf16 v[52:55], v[156:159], v[164:167], v[52:55]
	v_mfma_f32_16x16x32_bf16 v[40:43], v[148:151], v[172:175], v[40:43]
	v_mfma_f32_16x16x32_bf16 v[36:39], v[156:159], v[172:175], v[36:39]
	v_mfma_f32_16x16x32_bf16 v[24:27], v[148:151], v[180:183], v[24:27]
	v_mfma_f32_16x16x32_bf16 v[20:23], v[156:159], v[180:183], v[20:23]
	v_mfma_f32_16x16x32_bf16 v[8:11], v[148:151], v[188:191], v[8:11]
	v_mfma_f32_16x16x32_bf16 v[4:7], v[156:159], v[188:191], v[4:7]
	v_mfma_f32_16x16x32_bf16 v[56:59], v[152:155], v[168:171], v[56:59]
	v_mfma_f32_16x16x32_bf16 v[52:55], v[160:163], v[168:171], v[52:55]
	v_mfma_f32_16x16x32_bf16 v[40:43], v[152:155], v[176:179], v[40:43]
	v_mfma_f32_16x16x32_bf16 v[36:39], v[160:163], v[176:179], v[36:39]
	v_mfma_f32_16x16x32_bf16 v[24:27], v[152:155], v[184:187], v[24:27]
	v_mfma_f32_16x16x32_bf16 v[20:23], v[160:163], v[184:187], v[20:23]
	v_mfma_f32_16x16x32_bf16 v[8:11], v[152:155], v[192:195], v[8:11]
	v_mfma_f32_16x16x32_bf16 v[4:7], v[160:163], v[192:195], v[4:7]
	s_setprio 0
	s_barrier
	s_add_i32 s14, 0, 0x18000
	s_add_i32 s15, 0, 0x1c000
	v_add_u32_e32 v144, s14, v230
	v_add_u32_e32 v160, s15, v230
	ds_read_b128 v[124:127], v144
	ds_read_b128 v[128:131], v144 offset:1024
	ds_read_b128 v[136:139], v144 offset:2048
	ds_read_b128 v[144:147], v144 offset:3072
	ds_read_b128 v[148:151], v160
	ds_read_b128 v[152:155], v160 offset:1024
	ds_read_b128 v[156:159], v160 offset:2048
	ds_read_b128 v[160:163], v160 offset:3072
	s_add_u32 s12, s56, 0x40000
	s_addc_u32 s13, s57, 0
	s_mov_b32 m0, s81
	v_lshl_add_u64 v[204:205], s[12:13], 0, v[0:1]
	ds_read_b128 v[164:167], v243 offset:32768
	ds_read_b128 v[168:171], v243 offset:33792
	ds_read_b128 v[172:175], v243 offset:34816
	ds_read_b128 v[176:179], v243 offset:35840
	ds_read_b128 v[180:183], v243 offset:36864
	ds_read_b128 v[184:187], v243 offset:37888
	ds_read_b128 v[188:191], v243 offset:38912
	ds_read_b128 v[192:195], v243 offset:39936
	global_load_lds_dwordx4 v[204:205], off
	v_lshl_add_u64 v[204:205], s[12:13], 0, v[216:217]
	s_mov_b32 m0, s82
	s_nop 0
	global_load_lds_dwordx4 v[204:205], off
	s_waitcnt vmcnt(8)
	s_waitcnt lgkmcnt(0)
	s_barrier
	s_setprio 1
	s_waitcnt lgkmcnt(0)
	v_mfma_f32_16x16x32_bf16 v[140:143], v[124:127], v[164:167], v[140:143]
	v_mfma_f32_16x16x32_bf16 v[132:135], v[136:139], v[164:167], v[132:135]
	v_mfma_f32_16x16x32_bf16 v[112:115], v[124:127], v[172:175], v[112:115]
	v_mfma_f32_16x16x32_bf16 v[108:111], v[136:139], v[172:175], v[108:111]
	v_mfma_f32_16x16x32_bf16 v[96:99], v[124:127], v[180:183], v[96:99]
	v_mfma_f32_16x16x32_bf16 v[92:95], v[136:139], v[180:183], v[92:95]
	v_mfma_f32_16x16x32_bf16 v[80:83], v[124:127], v[188:191], v[80:83]
	v_mfma_f32_16x16x32_bf16 v[76:79], v[136:139], v[188:191], v[76:79]
	v_mfma_f32_16x16x32_bf16 v[140:143], v[128:131], v[168:171], v[140:143]
	v_mfma_f32_16x16x32_bf16 v[132:135], v[144:147], v[168:171], v[132:135]
	v_mfma_f32_16x16x32_bf16 v[112:115], v[128:131], v[176:179], v[112:115]
	v_mfma_f32_16x16x32_bf16 v[108:111], v[144:147], v[176:179], v[108:111]
	v_mfma_f32_16x16x32_bf16 v[96:99], v[128:131], v[184:187], v[96:99]
	v_mfma_f32_16x16x32_bf16 v[92:95], v[144:147], v[184:187], v[92:95]
	v_mfma_f32_16x16x32_bf16 v[80:83], v[128:131], v[192:195], v[80:83]
	v_mfma_f32_16x16x32_bf16 v[76:79], v[144:147], v[192:195], v[76:79]
	s_setprio 0
	s_setprio 1
	v_mfma_f32_16x16x32_bf16 v[120:123], v[148:151], v[164:167], v[120:123]
	v_mfma_f32_16x16x32_bf16 v[116:119], v[156:159], v[164:167], v[116:119]
	v_mfma_f32_16x16x32_bf16 v[104:107], v[148:151], v[172:175], v[104:107]
	v_mfma_f32_16x16x32_bf16 v[100:103], v[156:159], v[172:175], v[100:103]
	v_mfma_f32_16x16x32_bf16 v[88:91], v[148:151], v[180:183], v[88:91]
	v_mfma_f32_16x16x32_bf16 v[84:87], v[156:159], v[180:183], v[84:87]
	v_mfma_f32_16x16x32_bf16 v[72:75], v[148:151], v[188:191], v[72:75]
	v_mfma_f32_16x16x32_bf16 v[68:71], v[156:159], v[188:191], v[68:71]
	v_mfma_f32_16x16x32_bf16 v[120:123], v[152:155], v[168:171], v[120:123]
	v_mfma_f32_16x16x32_bf16 v[116:119], v[160:163], v[168:171], v[116:119]
	v_mfma_f32_16x16x32_bf16 v[104:107], v[152:155], v[176:179], v[104:107]
	v_mfma_f32_16x16x32_bf16 v[100:103], v[160:163], v[176:179], v[100:103]
	v_mfma_f32_16x16x32_bf16 v[88:91], v[152:155], v[184:187], v[88:91]
	v_mfma_f32_16x16x32_bf16 v[84:87], v[160:163], v[184:187], v[84:87]
	v_mfma_f32_16x16x32_bf16 v[72:75], v[152:155], v[192:195], v[72:75]
	v_mfma_f32_16x16x32_bf16 v[68:71], v[160:163], v[192:195], v[68:71]
	s_setprio 0
	s_barrier
	s_add_i32 s12, s14, s70
	v_lshl_add_u64 v[196:197], v[196:197], 0, s[68:69]
	s_mov_b32 m0, s12
	ds_read_b128 v[164:167], v243 offset:49152
	ds_read_b128 v[168:171], v243 offset:50176
	ds_read_b128 v[172:175], v243 offset:51200
	ds_read_b128 v[176:179], v243 offset:52224
	ds_read_b128 v[180:183], v243 offset:53248
	ds_read_b128 v[184:187], v243 offset:54272
	ds_read_b128 v[188:191], v243 offset:55296
	ds_read_b128 v[192:195], v243 offset:56320
	global_load_lds_dwordx4 v[196:197], off
	s_add_i32 m0, s12, 0x2000
	s_add_u32 s12, s40, 0x40080
	v_lshl_add_u64 v[196:197], v[198:199], 0, s[68:69]
	s_addc_u32 s13, s41, 0
	s_add_i32 s14, s15, s70
	global_load_lds_dwordx4 v[196:197], off
	v_lshl_add_u64 v[196:197], s[12:13], 0, v[2:3]
	s_mov_b32 m0, s14
	s_nop 0
	global_load_lds_dwordx4 v[196:197], off
	v_lshl_add_u64 v[196:197], s[12:13], 0, v[218:219]
	s_add_i32 m0, s14, 0x2000
	s_nop 0
	global_load_lds_dwordx4 v[196:197], off
	v_lshl_add_u64 v[196:197], v[200:201], 0, s[68:69]
	s_mov_b32 m0, s85
	s_nop 0
	global_load_lds_dwordx4 v[196:197], off
	v_lshl_add_u64 v[196:197], v[202:203], 0, s[68:69]
	s_mov_b32 m0, s87
	s_nop 0
	global_load_lds_dwordx4 v[196:197], off
	s_waitcnt vmcnt(8)
	s_waitcnt lgkmcnt(0)
	s_barrier
	s_setprio 1
	s_waitcnt lgkmcnt(0)
	v_mfma_f32_16x16x32_bf16 v[64:67], v[124:127], v[164:167], v[64:67]
	v_mfma_f32_16x16x32_bf16 v[60:63], v[136:139], v[164:167], v[60:63]
	v_mfma_f32_16x16x32_bf16 v[48:51], v[124:127], v[172:175], v[48:51]
	v_mfma_f32_16x16x32_bf16 v[44:47], v[136:139], v[172:175], v[44:47]
	v_mfma_f32_16x16x32_bf16 v[32:35], v[124:127], v[180:183], v[32:35]
	v_mfma_f32_16x16x32_bf16 v[28:31], v[136:139], v[180:183], v[28:31]
	v_mfma_f32_16x16x32_bf16 v[16:19], v[124:127], v[188:191], v[16:19]
	v_mfma_f32_16x16x32_bf16 v[12:15], v[136:139], v[188:191], v[12:15]
	v_mfma_f32_16x16x32_bf16 v[64:67], v[128:131], v[168:171], v[64:67]
	v_mfma_f32_16x16x32_bf16 v[60:63], v[144:147], v[168:171], v[60:63]
	v_mfma_f32_16x16x32_bf16 v[48:51], v[128:131], v[176:179], v[48:51]
	v_mfma_f32_16x16x32_bf16 v[44:47], v[144:147], v[176:179], v[44:47]
	v_mfma_f32_16x16x32_bf16 v[32:35], v[128:131], v[184:187], v[32:35]
	v_mfma_f32_16x16x32_bf16 v[28:31], v[144:147], v[184:187], v[28:31]
	v_mfma_f32_16x16x32_bf16 v[16:19], v[128:131], v[192:195], v[16:19]
	v_mfma_f32_16x16x32_bf16 v[12:15], v[144:147], v[192:195], v[12:15]
	s_setprio 0
	s_setprio 1
	v_mfma_f32_16x16x32_bf16 v[56:59], v[148:151], v[164:167], v[56:59]
	v_mfma_f32_16x16x32_bf16 v[52:55], v[156:159], v[164:167], v[52:55]
	v_mfma_f32_16x16x32_bf16 v[40:43], v[148:151], v[172:175], v[40:43]
	v_mfma_f32_16x16x32_bf16 v[36:39], v[156:159], v[172:175], v[36:39]
	v_mfma_f32_16x16x32_bf16 v[24:27], v[148:151], v[180:183], v[24:27]
	v_mfma_f32_16x16x32_bf16 v[20:23], v[156:159], v[180:183], v[20:23]
	v_mfma_f32_16x16x32_bf16 v[8:11], v[148:151], v[188:191], v[8:11]
	v_mfma_f32_16x16x32_bf16 v[4:7], v[156:159], v[188:191], v[4:7]
	v_mfma_f32_16x16x32_bf16 v[56:59], v[152:155], v[168:171], v[56:59]
	v_mfma_f32_16x16x32_bf16 v[52:55], v[160:163], v[168:171], v[52:55]
	v_mfma_f32_16x16x32_bf16 v[40:43], v[152:155], v[176:179], v[40:43]
	v_mfma_f32_16x16x32_bf16 v[36:39], v[160:163], v[176:179], v[36:39]
	v_mfma_f32_16x16x32_bf16 v[24:27], v[152:155], v[184:187], v[24:27]
	v_mfma_f32_16x16x32_bf16 v[20:23], v[160:163], v[184:187], v[20:23]
	v_mfma_f32_16x16x32_bf16 v[8:11], v[152:155], v[192:195], v[8:11]
	v_mfma_f32_16x16x32_bf16 v[4:7], v[160:163], v[192:195], v[4:7]
	s_setprio 0
	s_barrier
	s_add_i32 s11, s11, 2
	s_add_u32 s9, s9, 0x100
	s_addc_u32 s10, s10, 0
	s_add_u32 s38, s38, 0x100
	s_addc_u32 s39, s39, 0
	s_cmp_gt_u32 s11, 13
	s_cbranch_scc0 .LBB0_947
	s_lshl_b32 s98, s4, 8
	s_add_i32 s98, s98, s83
	s_lshl_b32 s99, s20, 8
	s_or_b32 s99, s99, s84
	v_and_b32_e32 v144, 15, v234
	v_lshrrev_b32_e32 v145, 4, v234
	v_add_u32_e32 v144, s98, v144
	v_lshl_add_u32 v145, v145, 3, s99
	v_lshlrev_b32_e32 v145, 1, v145
	v_lshl_add_u32 v146, v144, 12, v145
	global_load_dword v147, v146, s[24:25]
	global_load_dword v147, v146, s[24:25] offset:256
	s_add_u32 s100, s24, 0x10000
	s_addc_u32 s101, s25, 0
	global_load_dword v147, v146, s[100:101]
	global_load_dword v147, v146, s[100:101] offset:256
	s_add_u32 s100, s24, 0x20000
	s_addc_u32 s101, s25, 0
	global_load_dword v147, v146, s[100:101]
	global_load_dword v147, v146, s[100:101] offset:256
	s_add_u32 s100, s24, 0x30000
	s_addc_u32 s101, s25, 0
	global_load_dword v147, v146, s[100:101]
	global_load_dword v147, v146, s[100:101] offset:256
	s_add_u32 s100, s24, 0x80000
	s_addc_u32 s101, s25, 0
	global_load_dword v147, v146, s[100:101]
	global_load_dword v147, v146, s[100:101] offset:256
	s_add_u32 s100, s24, 0x90000
	s_addc_u32 s101, s25, 0
	global_load_dword v147, v146, s[100:101]
	global_load_dword v147, v146, s[100:101] offset:256
	s_add_u32 s100, s24, 0xa0000
	s_addc_u32 s101, s25, 0
	global_load_dword v147, v146, s[100:101]
	global_load_dword v147, v146, s[100:101] offset:256
	s_add_u32 s100, s24, 0xb0000
	s_addc_u32 s101, s25, 0
	global_load_dword v147, v146, s[100:101]
	global_load_dword v147, v146, s[100:101] offset:256
	s_and_b64 vcc, exec, s[46:47]
	s_cbranch_vccz .LBB0_950
	s_barrier

.LBB0_1134:
	s_add_u32 s40, s38, 0x100
	s_addc_u32 s41, s39, 0
	s_add_i32 s8, 0, 0x10000
	s_cmpk_eq_i32 s7, 0x54
	s_cselect_b32 s45, s61, s41
	s_cselect_b32 s44, s60, s40
	s_cselect_b32 s43, s63, s6
	s_cselect_b32 s42, s62, s5
	s_add_i32 s10, 0, 0x14000
	v_add_u32_e32 v112, s8, v242
	v_add_u32_e32 v148, s10, v242
	ds_read_b128 v[92:95], v112
	ds_read_b128 v[100:103], v112 offset:1024
	ds_read_b128 v[108:111], v112 offset:2048
	ds_read_b128 v[112:115], v112 offset:3072
	ds_read_b128 v[116:119], v148
	ds_read_b128 v[128:131], v148 offset:1024
	ds_read_b128 v[140:143], v148 offset:2048
	ds_read_b128 v[148:151], v148 offset:3072
	v_lshl_add_u64 v[196:197], s[38:39], 0, v[222:223]
	s_add_i32 m0, s83, 0xc000
	ds_read_b128 v[160:163], v245
	ds_read_b128 v[168:171], v245 offset:1024
	ds_read_b128 v[172:175], v245 offset:2048
	ds_read_b128 v[176:179], v245 offset:3072
	ds_read_b128 v[180:183], v245 offset:4096
	ds_read_b128 v[184:187], v245 offset:5120
	ds_read_b128 v[188:191], v245 offset:6144
	ds_read_b128 v[192:195], v245 offset:7168
	global_load_lds_dwordx4 v[196:197], off
	v_lshl_add_u64 v[196:197], s[38:39], 0, v[220:221]
	s_add_i32 m0, s83, 0xe000
	s_nop 0
	global_load_lds_dwordx4 v[196:197], off
	s_waitcnt vmcnt(8)
	s_waitcnt lgkmcnt(0)
	s_barrier
	s_setprio 1
	s_waitcnt lgkmcnt(0)
	v_mfma_f32_16x16x32_bf16 v[164:167], v[92:95], v[160:163], v[164:167]
	v_mfma_f32_16x16x32_bf16 v[156:159], v[108:111], v[160:163], v[156:159]
	v_mfma_f32_16x16x32_bf16 v[136:139], v[92:95], v[172:175], v[136:139]
	v_mfma_f32_16x16x32_bf16 v[132:135], v[108:111], v[172:175], v[132:135]
	v_mfma_f32_16x16x32_bf16 v[104:107], v[92:95], v[180:183], v[104:107]
	v_mfma_f32_16x16x32_bf16 v[96:99], v[108:111], v[180:183], v[96:99]
	v_mfma_f32_16x16x32_bf16 v[80:83], v[92:95], v[188:191], v[80:83]
	v_mfma_f32_16x16x32_bf16 v[76:79], v[108:111], v[188:191], v[76:79]
	v_mfma_f32_16x16x32_bf16 v[164:167], v[100:103], v[168:171], v[164:167]
	v_mfma_f32_16x16x32_bf16 v[156:159], v[112:115], v[168:171], v[156:159]
	v_mfma_f32_16x16x32_bf16 v[136:139], v[100:103], v[176:179], v[136:139]
	v_mfma_f32_16x16x32_bf16 v[132:135], v[112:115], v[176:179], v[132:135]
	v_mfma_f32_16x16x32_bf16 v[104:107], v[100:103], v[184:187], v[104:107]
	v_mfma_f32_16x16x32_bf16 v[96:99], v[112:115], v[184:187], v[96:99]
	v_mfma_f32_16x16x32_bf16 v[80:83], v[100:103], v[192:195], v[80:83]
	v_mfma_f32_16x16x32_bf16 v[76:79], v[112:115], v[192:195], v[76:79]
	s_setprio 0
	s_setprio 1
	v_mfma_f32_16x16x32_bf16 v[152:155], v[116:119], v[160:163], v[152:155]
	v_mfma_f32_16x16x32_bf16 v[144:147], v[140:143], v[160:163], v[144:147]
	v_mfma_f32_16x16x32_bf16 v[124:127], v[116:119], v[172:175], v[124:127]
	v_mfma_f32_16x16x32_bf16 v[120:123], v[140:143], v[172:175], v[120:123]
	v_mfma_f32_16x16x32_bf16 v[88:91], v[116:119], v[180:183], v[88:91]
	v_mfma_f32_16x16x32_bf16 v[84:87], v[140:143], v[180:183], v[84:87]
	v_mfma_f32_16x16x32_bf16 v[72:75], v[116:119], v[188:191], v[72:75]
	v_mfma_f32_16x16x32_bf16 v[68:71], v[140:143], v[188:191], v[68:71]
	v_mfma_f32_16x16x32_bf16 v[152:155], v[128:131], v[168:171], v[152:155]
	v_mfma_f32_16x16x32_bf16 v[144:147], v[148:151], v[168:171], v[144:147]
	v_mfma_f32_16x16x32_bf16 v[124:127], v[128:131], v[176:179], v[124:127]
	v_mfma_f32_16x16x32_bf16 v[120:123], v[148:151], v[176:179], v[120:123]
	v_mfma_f32_16x16x32_bf16 v[88:91], v[128:131], v[184:187], v[88:91]
	v_mfma_f32_16x16x32_bf16 v[84:87], v[148:151], v[184:187], v[84:87]
	v_mfma_f32_16x16x32_bf16 v[72:75], v[128:131], v[192:195], v[72:75]
	v_mfma_f32_16x16x32_bf16 v[68:71], v[148:151], v[192:195], v[68:71]
	s_setprio 0
	s_barrier
	s_add_i32 s8, s8, s82
	v_lshl_add_u64 v[196:197], s[42:43], 0, v[2:3]
	s_mov_b32 m0, s8
	ds_read_b128 v[160:163], v245 offset:16384
	ds_read_b128 v[168:171], v245 offset:17408
	ds_read_b128 v[172:175], v245 offset:18432
	ds_read_b128 v[176:179], v245 offset:19456
	ds_read_b128 v[180:183], v245 offset:20480
	ds_read_b128 v[184:187], v245 offset:21504
	ds_read_b128 v[188:191], v245 offset:22528
	ds_read_b128 v[192:195], v245 offset:23552
	global_load_lds_dwordx4 v[196:197], off
	s_add_i32 m0, s8, 0x2000
	s_add_u32 s8, s42, 0x160000
	v_lshl_add_u64 v[198:199], s[42:43], 0, v[218:219]
	s_addc_u32 s9, s43, 0
	s_add_i32 s10, s10, s82
	global_load_lds_dwordx4 v[198:199], off
	v_lshl_add_u64 v[200:201], s[8:9], 0, v[2:3]
	s_mov_b32 m0, s10
	v_lshl_add_u64 v[202:203], s[44:45], 0, v[216:217]
	global_load_lds_dwordx4 v[200:201], off
	v_lshl_add_u64 v[200:201], s[8:9], 0, v[218:219]
	s_add_i32 m0, s10, 0x2000
	s_nop 0
	global_load_lds_dwordx4 v[200:201], off
	v_lshl_add_u64 v[200:201], s[44:45], 0, v[0:1]
	s_mov_b32 m0, s83
	s_nop 0
	global_load_lds_dwordx4 v[200:201], off
	s_mov_b32 m0, s84
	s_nop 0
	global_load_lds_dwordx4 v[202:203], off
	s_waitcnt vmcnt(8)
	s_waitcnt lgkmcnt(0)
	s_barrier
	s_setprio 1
	s_waitcnt lgkmcnt(0)
	v_mfma_f32_16x16x32_bf16 v[64:67], v[92:95], v[160:163], v[64:67]
	v_mfma_f32_16x16x32_bf16 v[60:63], v[108:111], v[160:163], v[60:63]
	v_mfma_f32_16x16x32_bf16 v[48:51], v[92:95], v[172:175], v[48:51]
	v_mfma_f32_16x16x32_bf16 v[44:47], v[108:111], v[172:175], v[44:47]
	v_mfma_f32_16x16x32_bf16 v[32:35], v[92:95], v[180:183], v[32:35]
	v_mfma_f32_16x16x32_bf16 v[28:31], v[108:111], v[180:183], v[28:31]
	v_mfma_f32_16x16x32_bf16 v[16:19], v[92:95], v[188:191], v[16:19]
	v_mfma_f32_16x16x32_bf16 v[12:15], v[108:111], v[188:191], v[12:15]
	v_mfma_f32_16x16x32_bf16 v[64:67], v[100:103], v[168:171], v[64:67]
	v_mfma_f32_16x16x32_bf16 v[60:63], v[112:115], v[168:171], v[60:63]
	v_mfma_f32_16x16x32_bf16 v[48:51], v[100:103], v[176:179], v[48:51]
	v_mfma_f32_16x16x32_bf16 v[44:47], v[112:115], v[176:179], v[44:47]
	v_mfma_f32_16x16x32_bf16 v[32:35], v[100:103], v[184:187], v[32:35]
	v_mfma_f32_16x16x32_bf16 v[28:31], v[112:115], v[184:187], v[28:31]
	v_mfma_f32_16x16x32_bf16 v[16:19], v[100:103], v[192:195], v[16:19]
	v_mfma_f32_16x16x32_bf16 v[12:15], v[112:115], v[192:195], v[12:15]
	s_setprio 0
	s_setprio 1
	v_mfma_f32_16x16x32_bf16 v[56:59], v[116:119], v[160:163], v[56:59]
	v_mfma_f32_16x16x32_bf16 v[52:55], v[140:143], v[160:163], v[52:55]
	v_mfma_f32_16x16x32_bf16 v[40:43], v[116:119], v[172:175], v[40:43]
	v_mfma_f32_16x16x32_bf16 v[36:39], v[140:143], v[172:175], v[36:39]
	v_mfma_f32_16x16x32_bf16 v[24:27], v[116:119], v[180:183], v[24:27]
	v_mfma_f32_16x16x32_bf16 v[20:23], v[140:143], v[180:183], v[20:23]
	v_mfma_f32_16x16x32_bf16 v[8:11], v[116:119], v[188:191], v[8:11]
	v_mfma_f32_16x16x32_bf16 v[4:7], v[140:143], v[188:191], v[4:7]
	v_mfma_f32_16x16x32_bf16 v[56:59], v[128:131], v[168:171], v[56:59]
	v_mfma_f32_16x16x32_bf16 v[52:55], v[148:151], v[168:171], v[52:55]
	v_mfma_f32_16x16x32_bf16 v[40:43], v[128:131], v[176:179], v[40:43]
	v_mfma_f32_16x16x32_bf16 v[36:39], v[148:151], v[176:179], v[36:39]
	v_mfma_f32_16x16x32_bf16 v[24:27], v[128:131], v[184:187], v[24:27]
	v_mfma_f32_16x16x32_bf16 v[20:23], v[148:151], v[184:187], v[20:23]
	v_mfma_f32_16x16x32_bf16 v[8:11], v[128:131], v[192:195], v[8:11]
	v_mfma_f32_16x16x32_bf16 v[4:7], v[148:151], v[192:195], v[4:7]
	s_setprio 0
	s_barrier
	s_add_i32 s10, 0, 0x18000
	s_add_i32 s11, 0, 0x1c000
	v_add_u32_e32 v112, s10, v242
	v_add_u32_e32 v148, s11, v242
	ds_read_b128 v[92:95], v112
	ds_read_b128 v[100:103], v112 offset:1024
	ds_read_b128 v[108:111], v112 offset:2048
	ds_read_b128 v[112:115], v112 offset:3072
	ds_read_b128 v[116:119], v148
	ds_read_b128 v[128:131], v148 offset:1024
	ds_read_b128 v[140:143], v148 offset:2048
	ds_read_b128 v[148:151], v148 offset:3072
	s_add_u32 s8, s44, 0x160000
	s_addc_u32 s9, s45, 0
	s_mov_b32 m0, s85
	v_lshl_add_u64 v[204:205], s[8:9], 0, v[0:1]
	ds_read_b128 v[160:163], v245 offset:32768
	ds_read_b128 v[168:171], v245 offset:33792
	ds_read_b128 v[172:175], v245 offset:34816
	ds_read_b128 v[176:179], v245 offset:35840
	ds_read_b128 v[180:183], v245 offset:36864
	ds_read_b128 v[184:187], v245 offset:37888
	ds_read_b128 v[188:191], v245 offset:38912
	ds_read_b128 v[192:195], v245 offset:39936
	global_load_lds_dwordx4 v[204:205], off
	v_lshl_add_u64 v[204:205], s[8:9], 0, v[216:217]
	s_mov_b32 m0, s87
	s_nop 0
	global_load_lds_dwordx4 v[204:205], off
	s_waitcnt vmcnt(8)
	s_waitcnt lgkmcnt(0)
	s_barrier
	s_setprio 1
	s_waitcnt lgkmcnt(0)
	v_mfma_f32_16x16x32_bf16 v[164:167], v[92:95], v[160:163], v[164:167]
	v_mfma_f32_16x16x32_bf16 v[156:159], v[108:111], v[160:163], v[156:159]
	v_mfma_f32_16x16x32_bf16 v[136:139], v[92:95], v[172:175], v[136:139]
	v_mfma_f32_16x16x32_bf16 v[132:135], v[108:111], v[172:175], v[132:135]
	v_mfma_f32_16x16x32_bf16 v[104:107], v[92:95], v[180:183], v[104:107]
	v_mfma_f32_16x16x32_bf16 v[96:99], v[108:111], v[180:183], v[96:99]
	v_mfma_f32_16x16x32_bf16 v[80:83], v[92:95], v[188:191], v[80:83]
	v_mfma_f32_16x16x32_bf16 v[76:79], v[108:111], v[188:191], v[76:79]
	v_mfma_f32_16x16x32_bf16 v[164:167], v[100:103], v[168:171], v[164:167]
	v_mfma_f32_16x16x32_bf16 v[156:159], v[112:115], v[168:171], v[156:159]
	v_mfma_f32_16x16x32_bf16 v[136:139], v[100:103], v[176:179], v[136:139]
	v_mfma_f32_16x16x32_bf16 v[132:135], v[112:115], v[176:179], v[132:135]
	v_mfma_f32_16x16x32_bf16 v[104:107], v[100:103], v[184:187], v[104:107]
	v_mfma_f32_16x16x32_bf16 v[96:99], v[112:115], v[184:187], v[96:99]
	v_mfma_f32_16x16x32_bf16 v[80:83], v[100:103], v[192:195], v[80:83]
	v_mfma_f32_16x16x32_bf16 v[76:79], v[112:115], v[192:195], v[76:79]
	s_setprio 0
	s_setprio 1
	v_mfma_f32_16x16x32_bf16 v[152:155], v[116:119], v[160:163], v[152:155]
	v_mfma_f32_16x16x32_bf16 v[144:147], v[140:143], v[160:163], v[144:147]
	v_mfma_f32_16x16x32_bf16 v[124:127], v[116:119], v[172:175], v[124:127]
	v_mfma_f32_16x16x32_bf16 v[120:123], v[140:143], v[172:175], v[120:123]
	v_mfma_f32_16x16x32_bf16 v[88:91], v[116:119], v[180:183], v[88:91]
	v_mfma_f32_16x16x32_bf16 v[84:87], v[140:143], v[180:183], v[84:87]
	v_mfma_f32_16x16x32_bf16 v[72:75], v[116:119], v[188:191], v[72:75]
	v_mfma_f32_16x16x32_bf16 v[68:71], v[140:143], v[188:191], v[68:71]
	v_mfma_f32_16x16x32_bf16 v[152:155], v[128:131], v[168:171], v[152:155]
	v_mfma_f32_16x16x32_bf16 v[144:147], v[148:151], v[168:171], v[144:147]
	v_mfma_f32_16x16x32_bf16 v[124:127], v[128:131], v[176:179], v[124:127]
	v_mfma_f32_16x16x32_bf16 v[120:123], v[148:151], v[176:179], v[120:123]
	v_mfma_f32_16x16x32_bf16 v[88:91], v[128:131], v[184:187], v[88:91]
	v_mfma_f32_16x16x32_bf16 v[84:87], v[148:151], v[184:187], v[84:87]
	v_mfma_f32_16x16x32_bf16 v[72:75], v[128:131], v[192:195], v[72:75]
	v_mfma_f32_16x16x32_bf16 v[68:71], v[148:151], v[192:195], v[68:71]
	s_setprio 0
	s_barrier
	s_add_i32 s8, s10, s82
	v_lshl_add_u64 v[196:197], v[196:197], 0, s[68:69]
	s_mov_b32 m0, s8
	ds_read_b128 v[160:163], v245 offset:49152
	ds_read_b128 v[168:171], v245 offset:50176
	ds_read_b128 v[172:175], v245 offset:51200
	ds_read_b128 v[176:179], v245 offset:52224
	ds_read_b128 v[180:183], v245 offset:53248
	ds_read_b128 v[184:187], v245 offset:54272
	ds_read_b128 v[188:191], v245 offset:55296
	ds_read_b128 v[192:195], v245 offset:56320
	global_load_lds_dwordx4 v[196:197], off
	s_add_i32 m0, s8, 0x2000
	s_add_u32 s8, s42, 0x160080
	v_lshl_add_u64 v[196:197], v[198:199], 0, s[68:69]
	s_addc_u32 s9, s43, 0
	s_add_i32 s10, s11, s82
	global_load_lds_dwordx4 v[196:197], off
	v_lshl_add_u64 v[196:197], s[8:9], 0, v[2:3]
	s_mov_b32 m0, s10
	s_nop 0
	global_load_lds_dwordx4 v[196:197], off
	v_lshl_add_u64 v[196:197], s[8:9], 0, v[218:219]
	s_add_i32 m0, s10, 0x2000
	s_nop 0
	global_load_lds_dwordx4 v[196:197], off
	v_lshl_add_u64 v[196:197], v[200:201], 0, s[68:69]
	s_mov_b32 m0, s72
	s_nop 0
	global_load_lds_dwordx4 v[196:197], off
	v_lshl_add_u64 v[196:197], v[202:203], 0, s[68:69]
	s_mov_b32 m0, s88
	s_nop 0
	global_load_lds_dwordx4 v[196:197], off
	s_waitcnt vmcnt(8)
	s_waitcnt lgkmcnt(0)
	s_barrier
	s_setprio 1
	s_waitcnt lgkmcnt(0)
	v_mfma_f32_16x16x32_bf16 v[64:67], v[92:95], v[160:163], v[64:67]
	v_mfma_f32_16x16x32_bf16 v[60:63], v[108:111], v[160:163], v[60:63]
	v_mfma_f32_16x16x32_bf16 v[48:51], v[92:95], v[172:175], v[48:51]
	v_mfma_f32_16x16x32_bf16 v[44:47], v[108:111], v[172:175], v[44:47]
	v_mfma_f32_16x16x32_bf16 v[32:35], v[92:95], v[180:183], v[32:35]
	v_mfma_f32_16x16x32_bf16 v[28:31], v[108:111], v[180:183], v[28:31]
	v_mfma_f32_16x16x32_bf16 v[16:19], v[92:95], v[188:191], v[16:19]
	v_mfma_f32_16x16x32_bf16 v[12:15], v[108:111], v[188:191], v[12:15]
	v_mfma_f32_16x16x32_bf16 v[64:67], v[100:103], v[168:171], v[64:67]
	v_mfma_f32_16x16x32_bf16 v[60:63], v[112:115], v[168:171], v[60:63]
	v_mfma_f32_16x16x32_bf16 v[48:51], v[100:103], v[176:179], v[48:51]
	v_mfma_f32_16x16x32_bf16 v[44:47], v[112:115], v[176:179], v[44:47]
	v_mfma_f32_16x16x32_bf16 v[32:35], v[100:103], v[184:187], v[32:35]
	v_mfma_f32_16x16x32_bf16 v[28:31], v[112:115], v[184:187], v[28:31]
	v_mfma_f32_16x16x32_bf16 v[16:19], v[100:103], v[192:195], v[16:19]
	v_mfma_f32_16x16x32_bf16 v[12:15], v[112:115], v[192:195], v[12:15]
	s_setprio 0
	s_setprio 1
	v_mfma_f32_16x16x32_bf16 v[56:59], v[116:119], v[160:163], v[56:59]
	v_mfma_f32_16x16x32_bf16 v[52:55], v[140:143], v[160:163], v[52:55]
	v_mfma_f32_16x16x32_bf16 v[40:43], v[116:119], v[172:175], v[40:43]
	v_mfma_f32_16x16x32_bf16 v[36:39], v[140:143], v[172:175], v[36:39]
	v_mfma_f32_16x16x32_bf16 v[24:27], v[116:119], v[180:183], v[24:27]
	v_mfma_f32_16x16x32_bf16 v[20:23], v[140:143], v[180:183], v[20:23]
	v_mfma_f32_16x16x32_bf16 v[8:11], v[116:119], v[188:191], v[8:11]
	v_mfma_f32_16x16x32_bf16 v[4:7], v[140:143], v[188:191], v[4:7]
	v_mfma_f32_16x16x32_bf16 v[56:59], v[128:131], v[168:171], v[56:59]
	v_mfma_f32_16x16x32_bf16 v[52:55], v[148:151], v[168:171], v[52:55]
	v_mfma_f32_16x16x32_bf16 v[40:43], v[128:131], v[176:179], v[40:43]
	v_mfma_f32_16x16x32_bf16 v[36:39], v[148:151], v[176:179], v[36:39]
	v_mfma_f32_16x16x32_bf16 v[24:27], v[128:131], v[184:187], v[24:27]
	v_mfma_f32_16x16x32_bf16 v[20:23], v[148:151], v[184:187], v[20:23]
	v_mfma_f32_16x16x32_bf16 v[8:11], v[128:131], v[192:195], v[8:11]
	v_mfma_f32_16x16x32_bf16 v[4:7], v[148:151], v[192:195], v[4:7]
	s_setprio 0
	s_barrier
	s_add_i32 s7, s7, 2
	s_add_u32 s5, s5, 0x100
	s_addc_u32 s6, s6, 0
	s_cmpk_gt_u32 s7, 0x55
	s_mov_b64 s[38:39], s[40:41]
	s_cbranch_scc0 .LBB0_1134
	s_lshl_b32 s98, s4, 8
	s_add_i32 s98, s98, s66
	s_lshl_b32 s99, s20, 8
	s_or_b32 s99, s99, s67
	v_and_b32_e32 v168, 15, v234
	v_lshrrev_b32_e32 v169, 4, v234
	v_add_u32_e32 v168, s98, v168
	v_lshl_add_u32 v169, v169, 3, s99
	v_lshlrev_b32_e32 v169, 1, v169
	v_lshl_add_u32 v170, v168, 12, v169
	global_load_dword v171, v170, s[24:25]
	global_load_dword v171, v170, s[24:25] offset:256
	s_add_u32 s100, s24, 0x10000
	s_addc_u32 s101, s25, 0
	global_load_dword v171, v170, s[100:101]
	global_load_dword v171, v170, s[100:101] offset:256
	s_add_u32 s100, s24, 0x20000
	s_addc_u32 s101, s25, 0
	global_load_dword v171, v170, s[100:101]
	global_load_dword v171, v170, s[100:101] offset:256
	s_add_u32 s100, s24, 0x30000
	s_addc_u32 s101, s25, 0
	global_load_dword v171, v170, s[100:101]
	global_load_dword v171, v170, s[100:101] offset:256
	s_add_u32 s100, s24, 0x80000
	s_addc_u32 s101, s25, 0
	global_load_dword v171, v170, s[100:101]
	global_load_dword v171, v170, s[100:101] offset:256
	s_add_u32 s100, s24, 0x90000
	s_addc_u32 s101, s25, 0
	global_load_dword v171, v170, s[100:101]
	global_load_dword v171, v170, s[100:101] offset:256
	s_add_u32 s100, s24, 0xa0000
	s_addc_u32 s101, s25, 0
	global_load_dword v171, v170, s[100:101]
	global_load_dword v171, v170, s[100:101] offset:256
	s_add_u32 s100, s24, 0xb0000
	s_addc_u32 s101, s25, 0
	global_load_dword v171, v170, s[100:101]
	global_load_dword v171, v170, s[100:101] offset:256
	s_and_b64 vcc, exec, s[52:53]
	s_cbranch_vccz .LBB0_1137
	s_barrier
